# v8 + P9 work-queue ticket requested at the top of the unit and published at the bottom (round trip hidden behind the unit)
# speedup vs baseline: 1.0135x; 1.0015x over previous
; #define LAS __attribute__((address_space(3)))
; __device__ __forceinline__ int fresh_lane() { int ln; asm volatile("v_mbcnt_lo_u32_b32 %0, -1, 0\n\tv_mbcnt_hi_u32_b32 %0, -1, %0" : "=v"(ln)); return ln; }
; __device__ __forceinline__ int q_block(const Frame& F, int cw) {
;     volatile LAS int* slot = (volatile LAS int*)(F.lds + LDS_MISC + 64);
;     __syncthreads();
;     if (F.wave == 0 && fresh_lane() == 0) *slot = (int)__hip_atomic_fetch_add(F.ctl + cw, 1u, __ATOMIC_RELAXED, __HIP_MEMORY_SCOPE_AGENT);
;     __syncthreads();
;     return *slot;
; }
; template <unsigned MASK> __global__ void __launch_bounds__(NTHREADS, 2) fwd(Args A0) {
;     ...
;             { for (int u = q_block(F, cwb + 384); u < ((M / 64) * 8); u = q_block(F, cwb + 384)) { peer_score_unit(F, l, u); } }
.LBB0_2047:
	s_cmp_eq_u64 s[44:45], 0
	s_cbranch_scc1 .Lq_p9_top
	s_mov_b64 s[100:101], exec
	s_mov_b64 exec, 1
	v_mov_b32_e32 v150, 1
	global_atomic_add v150, v201, v150, s[48:49] sc0
	s_mov_b64 exec, s[100:101]

; #define LAS __attribute__((address_space(3)))
; __device__ __forceinline__ int fresh_lane() { int ln; asm volatile("v_mbcnt_lo_u32_b32 %0, -1, 0\n\tv_mbcnt_hi_u32_b32 %0, -1, %0" : "=v"(ln)); return ln; }
; __device__ __forceinline__ int q_block(const Frame& F, int cw) {
;     volatile LAS int* slot = (volatile LAS int*)(F.lds + LDS_MISC + 64);
;     __syncthreads();
;     if (F.wave == 0 && fresh_lane() == 0) *slot = (int)__hip_atomic_fetch_add(F.ctl + cw, 1u, __ATOMIC_RELAXED, __HIP_MEMORY_SCOPE_AGENT);
;     __syncthreads();
;     return *slot;
; }
; template <unsigned MASK> __global__ void __launch_bounds__(NTHREADS, 2) fwd(Args A0) {
;     ...
;             { for (int u = q_block(F, cwb + 384); u < ((M / 64) * 8); u = q_block(F, cwb + 384)) { peer_score_unit(F, l, u); } }
.LBB0_2051:
	s_or_b64 exec, exec, s[52:53]
	s_andn2_b64 vcc, exec, s[44:45]
	s_barrier
	s_barrier
	s_cbranch_vccnz .LBB0_2046
	s_waitcnt vmcnt(0)
	v_readfirstlane_b32 s4, v150
	v_mov_b32_e32 v1, s87
	s_nop 0
	v_mov_b32_e32 v0, s4
	ds_write_b32 v1, v0
	s_branch .LBB0_2046
